# v13 plus a virtual block id = XCC id + 8 x arrival rank on that XCC (from the census atomic), so XCD-locality of the static work order no longer depends on round-robin placement
# speedup vs baseline: 1.0154x; 1.0080x over previous
_Z10fwd_kernel6Params:
	s_load_dwordx4 s[28:31], s[0:1], 0xa0
	s_load_dwordx2 s[92:93], s[0:1], 0xb0
	s_add_u32 s6, s0, 0xb0
	v_and_b32_e32 v164, 0x3ff, v0
	s_mov_b32 s70, s2
	s_addc_u32 s7, s1, 0
	v_readfirstlane_b32 s81, v164
	v_cmp_gt_u32_e32 vcc, 64, v164
	s_and_saveexec_b64 s[4:5], vcc
	v_lshl_add_u32 v1, v164, 2, 0
	v_add_u32_e32 v1, 0x20000, v1
	v_mov_b32_e32 v2, 0
	ds_write_b32 v1, v2
	s_or_b64 exec, exec, s[4:5]
	s_waitcnt lgkmcnt(0)
	s_barrier
	s_add_u32 s78, s30, 0x1000
	s_getreg_b32 s2, hwreg(HW_REG_XCC_ID, 0, 4)
	s_addc_u32 s79, s31, 0
	s_and_b32 s80, s2, 15
	v_cmp_eq_u32_e64 s[84:85], 0, v164
	s_and_saveexec_b64 s[4:5], s[84:85]
	s_cbranch_execz .LBB0_5
	s_mov_b64 s[8:9], exec
	v_mbcnt_lo_u32_b32 v1, s8, 0
	v_mbcnt_hi_u32_b32 v1, s9, v1
	v_cmp_eq_u32_e32 vcc, 0, v1
	s_and_b64 s[2:3], exec, vcc
	s_mov_b64 exec, s[2:3]
	s_cbranch_execz .LBB0_5
	s_lshl_b32 s2, s80, 8
	s_bcnt1_i32_b64 s3, s[8:9]
	v_mov_b32_e32 v1, s2
	v_mov_b32_e32 v2, s3
	global_atomic_add v3, v1, v2, s[78:79] offset:1024 sc0
	s_waitcnt vmcnt(0)
	v_lshl_add_u32 v3, v3, 3, s80
	v_mov_b32_e32 v1, 0x20020
	ds_write_b32 v1, v3
.LBB0_5:
	s_or_b64 exec, exec, s[4:5]
	s_waitcnt lgkmcnt(0)
	s_barrier
	v_mov_b32_e32 v1, 0x20020
	ds_read_b32 v1, v1
	s_waitcnt lgkmcnt(0)
	s_nop 0
	v_readfirstlane_b32 s70, v1
	s_nop 3
	s_lshr_b32 s94, s81, 6
	s_lshl_b32 s2, s70, 3
	s_add_i32 s4, s94, s2
	s_lshl_b32 s82, s92, 3
	s_add_u32 s20, s30, 0x400000
	s_addc_u32 s21, s31, 0
	s_lshl_b32 s2, s94, 14
	v_and_b32_e32 v138, 63, v164
	s_add_i32 s3, s2, 0
	s_mov_b32 s2, s4
	s_cmpk_gt_i32 s4, 0x4ff
	v_writelane_b32 v240, s2, 0
	v_and_b32_e32 v165, 31, v164
	v_lshrrev_b32_e32 v139, 5, v138
	v_lshrrev_b32_e32 v166, 3, v138
	v_writelane_b32 v240, s3, 1
	s_cbranch_scc1 .LBB0_12
	s_load_dwordx2 s[4:5], s[0:1], 0x50
	s_load_dwordx2 s[8:9], s[0:1], 0x60
	v_lshlrev_b32_e32 v2, 3, v138
	v_and_b32_e32 v1, 3, v164
	v_and_or_b32 v1, v2, 32, v1
	v_and_b32_e32 v2, 56, v2
	v_lshl_add_u32 v6, v165, 2, s3
	v_mul_u32_u24_e32 v7, 0x84, v139
	v_mul_u32_u24_e32 v8, 0x84, v2
	v_lshlrev_b32_e32 v2, 1, v2
	v_mov_b32_e32 v3, 0
	v_readlane_b32 s10, v240, 0
	v_lshl_add_u64 v[4:5], s[20:21], 0, v[2:3]
	v_lshlrev_b32_e32 v2, 2, v166
	v_readlane_b32 s11, v240, 1
	v_add_u32_e32 v14, v6, v7
	v_add3_u32 v10, s3, v8, v2
	v_or_b32_e32 v11, 8, v166
	v_or_b32_e32 v12, 16, v166
	v_or_b32_e32 v13, 24, v166
	s_lshl_b32 s2, s10, 5
	s_lshl_b32 s14, s82, 5
	s_lshl_b32 s15, s10, 2
	s_lshl_b32 s16, s82, 2
	s_mov_b32 s11, 0
	v_add_u32_e32 v15, 0x400, v14
	v_add_u32_e32 v16, 0x800, v14
	v_add_u32_e32 v17, 0xc00, v14
	v_add_u32_e32 v18, 0x1000, v14
	v_add_u32_e32 v19, 0x1400, v14
	v_add_u32_e32 v20, 0x1800, v14
	v_add_u32_e32 v21, 0x1c00, v14
	s_mov_b32 s17, s10
	s_branch .LBB0_8
